# non-temporal hint on single-use streaming loads (prologue x rows, cache_k/cache_v rows, final_norm residual rows), on top of v20
# speedup vs baseline: 1.0138x; 1.0032x over previous
; DI unsigned pk2(float lo, float hi) { unsigned r; asm volatile("v_cvt_pk_bf16_f32 %0, %1, %2" : "=v"(r) : "v"(lo), "v"(hi)); return r; }
; DI float bflo(unsigned u) { return __uint_as_float(u << 16); }
; DI float bfhi(unsigned u) { return __uint_as_float(u & 0xffff0000u); }
; DI void phase_prologue(const Prm& p, LAS unsigned char* lds, int tid, int lane, int wave) {
;     ...
;     for (int row = gw; row < NT; row += NGW) {
;         const float* src;
;         if (row < NTP) { const int b = row / TP, t = row - b * TP; src = t < 16 ? p.meta + (size_t)t * 1024 : p.x_prompt + ((size_t)b * 4096 + (t - 16)) * 1024; }
;         else src = p.x_sample + (size_t)(row - NTP) * 1024;
;         float ss = 0.f;
; #pragma unroll
;         for (int j = 0; j < 4; ++j) { const f32x4 v = ((const f32x4*)src)[lane + 64 * j]; u32x2 o; o.x = pk2(v.x, v.y); o.y = pk2(v.z, v.w);
;             const float a0 = bflo(o.x), a1 = bfhi(o.x), a2 = bflo(o.y), a3 = bfhi(o.y); ss += (a0 * a0 + a1 * a1) + (a2 * a2 + a3 * a3);
;             ((u32x2*)(p.XB + (size_t)row * 1024))[lane + 64 * j] = o; }
;         ss = wave_sum(ss);
;         if (lane < 16) p.SSQ[(size_t)row * 16 + lane] = lane == 0 ? ss : 0.f;
;         if (lane == 0) p.RINV[row] = rsqrtf(ss * (1.f / 1024.f) + EPSN);
;     }
.LBB0_76:
	s_cmp_lg_u32 s98, 0
	s_cbranch_scc1 .Ltr_return
	s_load_dwordx16 s[36:51], s[0:1], 0x0
	v_lshlrev_b32_e32 v2, 2, v152
	v_lshlrev_b32_e32 v156, 3, v152
	s_waitcnt lgkmcnt(0)
	v_writelane_b32 v254, s36, 54
	s_nop 1
	v_writelane_b32 v254, s37, 55
	v_writelane_b32 v254, s38, 56
	v_writelane_b32 v254, s39, 57
	v_writelane_b32 v254, s40, 58
	v_writelane_b32 v254, s41, 59
	v_writelane_b32 v254, s42, 60
	v_writelane_b32 v255, s46, 0
	v_writelane_b32 v254, s43, 61
	v_writelane_b32 v255, s47, 1
	v_writelane_b32 v254, s44, 62
	v_writelane_b32 v255, s48, 2
	v_writelane_b32 v254, s45, 63
	v_writelane_b32 v255, s49, 3
	v_writelane_b32 v255, s50, 4
	v_readlane_b32 s2, v254, 52
	v_writelane_b32 v255, s51, 5
	s_cmp_gt_i32 s2, 0x827f
	v_readlane_b32 s3, v254, 53
	s_cbranch_scc1 .LBB0_90
	s_load_dwordx4 s[36:39], s[0:1], 0x140
	v_readlane_b32 s8, v254, 52
	s_mov_b32 s28, s8
	s_ashr_i32 s29, s28, 31
	s_add_i32 s8, s8, 0xffff7f80
	s_lshl_b64 s[24:25], s[28:29], 2
	s_waitcnt lgkmcnt(0)
	s_add_u32 s24, s36, s24
	s_addc_u32 s25, s37, s25
	s_load_dwordx16 s[36:51], s[0:1], 0x100
	v_readlane_b32 s26, v254, 50
	v_readlane_b32 s27, v254, 51
	s_mov_b32 s30, s26
	s_ashr_i32 s31, s26, 31
	s_lshl_b64 s[26:27], s[30:31], 2
	s_lshl_b64 s[34:35], s[28:29], 6
	s_waitcnt lgkmcnt(0)
	s_add_u32 s34, s50, s34
	v_mov_b32_e32 v3, 0
	s_addc_u32 s35, s51, s35
	s_mov_b32 s7, 0
	v_lshl_add_u64 v[4:5], s[34:35], 0, v[2:3]
	s_lshl_b64 s[36:37], s[30:31], 6
	s_mov_b32 s6, s28
	s_lshl_b64 s[34:35], s[28:29], 11
	v_readlane_b32 s9, v254, 53
	v_writelane_b32 v254, s6, 52
	s_add_u32 s34, s48, s34
	v_mbcnt_lo_u32_b32 v8, -1, 0
	v_writelane_b32 v254, s7, 53
	v_mov_b32_e32 v157, v3
	s_addc_u32 s35, s49, s35
	s_mov_b32 s6, s30
	v_mbcnt_hi_u32_b32 v8, -1, v8
	v_lshl_add_u64 v[6:7], s[34:35], 0, v[156:157]
	s_mov_b64 s[34:35], 0x400
	v_writelane_b32 v254, s6, 50
	v_and_b32_e32 v9, 64, v8
	v_cmp_gt_u32_e64 s[2:3], 16, v152
	v_cmp_eq_u32_e64 s[4:5], 0, v152
	v_lshl_add_u64 v[6:7], v[6:7], 0, s[34:35]
	v_writelane_b32 v254, s7, 51
	s_lshl_b64 s[38:39], s[30:31], 11
	v_lshlrev_b32_e32 v1, 4, v152
	v_add_u32_e32 v9, 64, v9
	v_xor_b32_e32 v10, 1, v8
	v_xor_b32_e32 v11, 2, v8
	v_xor_b32_e32 v12, 4, v8
	v_xor_b32_e32 v13, 8, v8
	v_xor_b32_e32 v14, 16, v8
	v_xor_b32_e32 v15, 32, v8
	v_mov_b32_e32 v16, 0x358637bd
	s_load_dwordx2 s[48:49], s[0:1], 0x0
	s_load_dwordx2 s[50:51], s[0:1], 0x8
	s_load_dwordx2 s[52:53], s[0:1], 0x38
	v_readlane_b32 s54, v254, 50
	s_mov_b32 s55, 1
	s_add_i32 s6, s8, 0x8080
	s_waitcnt lgkmcnt(0)
	s_mul_hi_u32 s40, s6, 0xff011
	s_mul_i32 s41, s40, 0x1010
	s_sub_i32 s41, s6, s41
	s_sub_i32 s42, s41, 16
	s_lshl_b32 s43, s40, 12
	s_add_i32 s42, s42, s43
	s_cmp_lt_i32 s41, 16
	s_cselect_b32 s42, s41, s42
	s_cselect_b32 s34, s52, s48
	s_cselect_b32 s35, s53, s49
	s_sub_i32 s43, s6, 0x8080
	s_cmp_gt_i32 s6, 0x807f
	s_cselect_b32 s42, s43, s42
	s_cselect_b32 s34, s50, s34
	s_cselect_b32 s35, s51, s35
	s_mov_b32 s43, 0
	s_lshl_b64 s[42:43], s[42:43], 12
	s_add_u32 s34, s34, s42
	s_addc_u32 s35, s35, s43
	global_load_dwordx4 v[102:105], v1, s[34:35] nt
	global_load_dwordx4 v[106:109], v1, s[34:35] offset:1024 nt
	global_load_dwordx4 v[110:113], v1, s[34:35] offset:2048 nt
	global_load_dwordx4 v[114:117], v1, s[34:35] offset:3072 nt
.Lrw_loop:
	s_add_i32 s56, s8, s54
	s_add_i32 s6, s56, 0x8080
	s_cmp_gt_i32 s6, 0x827f
	s_cbranch_scc1 .Lrw_nonext
	s_mul_hi_u32 s40, s6, 0xff011
	s_mul_i32 s41, s40, 0x1010
	s_sub_i32 s41, s6, s41
	s_sub_i32 s42, s41, 16
	s_lshl_b32 s43, s40, 12
	s_add_i32 s42, s42, s43
	s_cmp_lt_i32 s41, 16
	s_cselect_b32 s42, s41, s42
	s_cselect_b32 s34, s52, s48
	s_cselect_b32 s35, s53, s49
	s_sub_i32 s43, s6, 0x8080
	s_cmp_gt_i32 s6, 0x807f
	s_cselect_b32 s42, s43, s42
	s_cselect_b32 s34, s50, s34
	s_cselect_b32 s35, s51, s35
	s_mov_b32 s43, 0
	s_lshl_b64 s[42:43], s[42:43], 12
	s_add_u32 s34, s34, s42
	s_addc_u32 s35, s35, s43
	global_load_dwordx4 v[118:121], v1, s[34:35] nt
	global_load_dwordx4 v[122:125], v1, s[34:35] offset:1024 nt
	global_load_dwordx4 v[126:129], v1, s[34:35] offset:2048 nt
	global_load_dwordx4 v[130:133], v1, s[34:35] offset:3072 nt
	s_cmp_eq_u32 s55, 0
	s_cbranch_scc1 .Lrw_compute
	s_mov_b32 s55, 0
	s_waitcnt vmcnt(4)
	s_branch .Lrw_compute

; DI unsigned pk2(float lo, float hi) { unsigned r; asm volatile("v_cvt_pk_bf16_f32 %0, %1, %2" : "=v"(r) : "v"(lo), "v"(hi)); return r; }
; DI unsigned short f2bf(float f) { return (unsigned short)(pk2(f, 0.f) & 0xffffu); }
; DI size_t kf_index(int seqh, int nkt, int key, int d) { return ((((size_t)seqh * nkt + (key >> 5)) * 8 + (d >> 4)) * 64 + ((key & 31) + 32 * ((d >> 3) & 1))) * 8 + (d & 7); }
; DI void cache_convert(const Prm& p, int gtid, int GT) {
;     for (size_t i = (size_t)gtid; i < (size_t)8 * 1024 * 256; i += (size_t)GT) {
;         const size_t row = i >> 8; const int c4 = (int)(i & 255) * 4, b = (int)(row >> 10), pos = (int)(row & 1023), h = c4 >> 7, d = c4 & 127;
;         const f32x4 k = *(const f32x4*)(p.cache_k + row * 1024 + c4); u32x2 o; o.x = pk2(k.x, k.y); o.y = pk2(k.z, k.w);
;         *(u32x2*)(p.KS + kf_index(b * 8 + h, 34, pos, d)) = o;
;         const f32x4 v = *(const f32x4*)(p.cache_v + row * 1024 + c4); bf16_t* vt = p.VTS + vf_index(b * 8 + h, 34, pos, d);
;         vt[0] = f2bf(v.x); vt[8] = f2bf(v.y); vt[16] = f2bf(v.z); vt[24] = f2bf(v.w); }
; __global__ void __launch_bounds__(512, 2) fwd_megakernel(Prm p) {
;     ...
;     if (gridDim.x > 36) { if (blockIdx.x >= 36) cache_convert(p, (blockIdx.x - 36) * 512 + tid, (gridDim.x - 36) * 512); } else cache_convert(p, gtid, GT);
.LBB0_2043:
	s_cmp_lt_u32 s84, 36
	s_cbranch_scc1 .LBB0_2048
	v_add_u32_e32 v0, 0xffffb800, v162
	s_mov_b32 s0, 0x200000
	v_cmp_gt_u32_e32 vcc, s0, v0
	s_and_saveexec_b64 s[0:1], vcc
	v_readlane_b32 s12, v254, 0
	v_readlane_b32 s14, v254, 2
	v_readlane_b32 s15, v254, 3
	v_readlane_b32 s18, v254, 6
	v_readlane_b32 s19, v254, 7
	v_readlane_b32 s13, v254, 1
	v_readlane_b32 s16, v254, 4
	v_readlane_b32 s17, v254, 5
	s_cbranch_execz .LBB0_2047
	s_add_i32 s8, s40, 0xffffb800
	v_mov_b32_e32 v1, 0
	s_lshl_b32 s2, s88, 11
	s_ashr_i32 s9, s8, 31
	v_lshlrev_b32_e32 v4, 2, v0
	s_add_i32 s2, s2, 0xfffee000
	s_mov_b64 s[10:11], 0
	s_mov_b64 s[12:13], 0x1fffff
	v_mov_b64_e32 v[2:3], v[0:1]
	v_lshlrev_b64 v[20:21], 4, v[2:3]
	s_lshl_b64 s[4:5], s[8:9], 4
	v_lshl_add_u64 v[22:23], s[48:49], 0, v[20:21]
	v_lshl_add_u64 v[20:21], s[46:47], 0, v[20:21]
	global_load_dwordx4 v[24:27], v[20:21], off nt
	global_load_dwordx4 v[28:31], v[22:23], off nt
	s_waitcnt vmcnt(0)
.Lcc_loop:
	v_cvt_pk_bf16_f32 v32, v24, v25
	v_cvt_pk_bf16_f32 v33, v26, v27
	v_cvt_pk_bf16_f32 v34, v28, v1
	v_cvt_pk_bf16_f32 v35, v29, v1
	v_cvt_pk_bf16_f32 v36, v30, v1
	v_cvt_pk_bf16_f32 v37, v31, v1
	v_lshl_add_u64 v[38:39], v[2:3], 0, s[8:9]
	s_mov_b64 s[6:7], exec
	v_cmp_lt_u64_e32 vcc, s[12:13], v[38:39]
	v_lshl_add_u64 v[20:21], v[20:21], 0, s[4:5]
	v_lshl_add_u64 v[22:23], v[22:23], 0, s[4:5]
	s_nop 1
	s_or_b64 s[10:11], vcc, s[10:11]
	s_andn2_b64 exec, exec, s[10:11]
	s_cbranch_execz .Lcc_nopf
	global_load_dwordx4 v[24:27], v[20:21], off nt
	global_load_dwordx4 v[28:31], v[22:23], off nt

; DI float bflo(unsigned u) { return __uint_as_float(u << 16); }
; DI float bfhi(unsigned u) { return __uint_as_float(u & 0xffff0000u); }
; DI void final_norm(const Prm& p, int gw, int NGW, int lane) {
;     for (int r = gw; r < 32768 + 512; r += NGW) {
;         int grow; float* dst;
;         if (r < 32768) { const int b = r >> 12, t = r & 4095; grow = b * TP + 16 + t; dst = p.out + O_YP + (size_t)r * 1024; } else { grow = NTP + (r - 32768); dst = p.out + O_YS + (size_t)(r - 32768) * 1024; }
;         u32x2 x[4];
; #pragma unroll
;         for (int j = 0; j < 4; ++j) x[j] = ((const u32x2*)(p.XB + (size_t)grow * 1024))[lane + 64 * j];
;         const float rr = row_rinv(p.SSQ, grow);
; #pragma unroll
;         for (int j = 0; j < 4; ++j) { f32x4 v; v.x = bflo(x[j].x); v.y = bfhi(x[j].x); v.z = bflo(x[j].y); v.w = bfhi(x[j].y); ((f32x4*)dst)[lane + 64 * j] = v * rr * ((const f32x4*)p.ln_final)[lane + 64 * j]; }
.LBB0_2747:
	s_or_b64 exec, exec, s[0:1]
	s_cmp_gt_i32 s34, 0x81ff
	s_waitcnt lgkmcnt(0)
	s_barrier
	s_cbranch_scc1 .LBB0_2754
	v_readlane_b32 s0, v254, 12
	v_readlane_b32 s8, v254, 20
	v_readlane_b32 s1, v254, 13
	v_readlane_b32 s4, v254, 16
	v_readlane_b32 s5, v254, 17
	v_readlane_b32 s6, v254, 18
	v_readlane_b32 s7, v254, 19
	v_readlane_b32 s9, v254, 21
	v_readlane_b32 s10, v254, 22
	v_readlane_b32 s11, v254, 23
	v_readlane_b32 s12, v254, 24
	v_readlane_b32 s13, v254, 25
	v_readlane_b32 s14, v254, 26
	v_readlane_b32 s15, v254, 27
	s_add_u32 s0, s8, 0x8000000
	v_mov_b32_e32 v1, 0
	s_addc_u32 s1, s9, 0
	v_readlane_b32 s4, v254, 28
	v_lshlrev_b32_e32 v0, 4, v152
	v_readlane_b32 s3, v254, 15
	v_mov_b32_e32 v157, v1
	v_readlane_b32 s12, v254, 36
	v_readlane_b32 s13, v254, 37
	v_readlane_b32 s16, v254, 40
	v_readlane_b32 s17, v254, 41
	v_lshl_add_u64 v[2:3], s[40:41], 0, v[0:1]
	s_ashr_i32 s35, s34, 31
	v_lshl_add_u64 v[4:5], s[16:17], 0, v[156:157]
	s_ashr_i32 s12, s36, 31
	s_mov_b32 s3, 0
	v_mov_b32_e32 v0, 0x358637bd
	s_mov_b32 s13, 0x800000
	v_lshlrev_b32_e32 v6, 4, v152
	v_readlane_b32 s2, v254, 14
	v_readlane_b32 s5, v254, 29
	v_readlane_b32 s6, v254, 30
	v_readlane_b32 s7, v254, 31
	v_readlane_b32 s8, v254, 32
	v_readlane_b32 s9, v254, 33
	v_readlane_b32 s10, v254, 34
	v_readlane_b32 s11, v254, 35
	v_readlane_b32 s14, v254, 38
	v_readlane_b32 s15, v254, 39
	v_readlane_b32 s18, v254, 42
	v_readlane_b32 s19, v254, 43
	v_readlane_b32 s20, v254, 20
	v_readlane_b32 s21, v254, 21
	v_readlane_b32 s22, v254, 42
	v_readlane_b32 s23, v254, 43
	global_load_dwordx4 v[40:43], v[2:3], off
	global_load_dwordx4 v[44:47], v[2:3], off offset:1024
	global_load_dwordx4 v[48:51], v[2:3], off offset:2048
	global_load_dwordx4 v[52:55], v[2:3], off offset:3072
	s_nop 4
	s_cmpk_gt_i32 s34, 0x7fff
	s_cselect_b32 s24, s0, s20
	s_cselect_b32 s25, s1, s21
	s_cselect_b32 s14, 0x8000, 0
	s_cselect_b32 s15, 1, 0
	s_sub_i32 s16, s34, s14
	s_mov_b32 s17, 0
	s_ashr_i32 s18, s34, 12
	s_mulk_i32 s18, 0x1010
	s_and_b32 s19, s34, 0xfff
	s_add_i32 s18, s18, s19
	s_add_i32 s18, s18, 16
	s_add_i32 s19, s34, 0x80
	s_cmp_lg_u32 s15, 0
	s_cselect_b32 s26, s19, s18
	s_lshl_b64 s[16:17], s[16:17], 12
	s_add_u32 s24, s24, s16
	s_addc_u32 s25, s25, s17
	s_mov_b32 s16, s26
	s_mov_b32 s17, 0
	s_lshl_b64 s[18:19], s[16:17], 11
	s_lshl_b64 s[16:17], s[16:17], 6
	s_add_u32 s6, s22, s16
	s_addc_u32 s7, s23, s17
	v_lshl_add_u64 v[56:57], v[4:5], 0, s[18:19]
	global_load_dwordx2 v[30:31], v[56:57], off nt
	global_load_dwordx2 v[32:33], v[56:57], off offset:512 nt
	global_load_dwordx2 v[34:35], v[56:57], off offset:1024 nt
	global_load_dwordx2 v[36:37], v[56:57], off offset:1536 nt
	global_load_dwordx4 v[8:11], v1, s[6:7]
	global_load_dwordx4 v[12:15], v1, s[6:7] offset:16
	global_load_dwordx4 v[16:19], v1, s[6:7] offset:32
	global_load_dwordx4 v[20:23], v1, s[6:7] offset:48
.Lfn_loop:
	s_add_i32 s37, s34, s36
	s_cmp_lt_i32 s37, 0x8200
	s_cbranch_scc0 .Lfn_nonext
	s_cmpk_gt_i32 s37, 0x7fff
	s_cselect_b32 s28, s0, s20
	s_cselect_b32 s29, s1, s21
	s_cselect_b32 s14, 0x8000, 0
	s_cselect_b32 s15, 1, 0
	s_sub_i32 s16, s37, s14
	s_mov_b32 s17, 0
	s_ashr_i32 s18, s37, 12
	s_mulk_i32 s18, 0x1010
	s_and_b32 s19, s37, 0xfff
	s_add_i32 s18, s18, s19
	s_add_i32 s18, s18, 16
	s_add_i32 s19, s37, 0x80
	s_cmp_lg_u32 s15, 0
	s_cselect_b32 s27, s19, s18
	s_lshl_b64 s[16:17], s[16:17], 12
	s_add_u32 s28, s28, s16
	s_addc_u32 s29, s29, s17
	s_mov_b32 s16, s27
	s_mov_b32 s17, 0
	s_lshl_b64 s[18:19], s[16:17], 11
	s_lshl_b64 s[16:17], s[16:17], 6
	s_add_u32 s6, s22, s16
	s_addc_u32 s7, s23, s17
	v_lshl_add_u64 v[56:57], v[4:5], 0, s[18:19]
	global_load_dwordx2 v[60:61], v[56:57], off nt
	global_load_dwordx2 v[62:63], v[56:57], off offset:512 nt
	global_load_dwordx2 v[64:65], v[56:57], off offset:1024 nt
	global_load_dwordx2 v[66:67], v[56:57], off offset:1536 nt
	global_load_dwordx4 v[68:71], v1, s[6:7]
	global_load_dwordx4 v[72:75], v1, s[6:7] offset:16
	global_load_dwordx4 v[76:79], v1, s[6:7] offset:32
	global_load_dwordx4 v[80:83], v1, s[6:7] offset:48
	s_waitcnt vmcnt(8)
	s_branch .Lfn_compute
